# v1 plus: row-sum adds of the attention steady loop split into two independent chains (byte-neutral)
# speedup vs baseline: 1.0024x; 1.0024x over previous
.LBB0_311:
	s_mov_b32 s37, s36
	s_mov_b32 s4, s33
	s_mov_b32 s1, s42
	v_add_u32_e32 v209, s5, v252
	ds_read_b64_tr_b16 v[216:217], v209 offset:24576
	ds_read_b64_tr_b16 v[218:219], v209 offset:25088
	v_add_f32_e32 v65, v96, v97
	v_add_f32_e32 v224, v98, v99
	v_add_f32_e32 v65, v100, v65
	v_add_f32_e32 v224, v101, v224
	s_nop 0
	v_cvt_pk_bf16_f32 v172, v96, v97
	v_cvt_pk_bf16_f32 v173, v98, v99
	s_waitcnt lgkmcnt(9)
	v_mfma_f32_32x32x16_bf16 v[128:143], v[204:207], v[156:159], v[230:245]
	ds_read_b64_tr_b16 v[204:205], v209 offset:28672
	ds_read_b64_tr_b16 v[206:207], v209 offset:29184
	v_add_f32_e32 v65, v102, v65
	v_add_f32_e32 v224, v103, v224
	v_add_f32_e32 v65, v104, v65
	v_add_f32_e32 v224, v105, v224
	v_cvt_pk_bf16_f32 v174, v100, v101
	v_cvt_pk_bf16_f32 v175, v102, v103
	s_waitcnt lgkmcnt(10)
	v_mfma_f32_32x32x16_bf16 v[112:127], v[200:203], v[156:159], v[230:245]
	ds_read_b64_tr_b16 v[74:75], v209 offset:25600
	ds_read_b64_tr_b16 v[76:77], v209 offset:26112
	v_add_f32_e32 v65, v106, v65
	v_add_f32_e32 v224, v107, v224
	v_add_f32_e32 v65, v108, v65
	v_add_f32_e32 v224, v109, v224
	v_cvt_pk_bf16_f32 v168, v104, v105
	v_cvt_pk_bf16_f32 v169, v106, v107
	s_waitcnt lgkmcnt(11)
	v_mfma_f32_32x32x16_bf16 v[128:143], v[196:199], v[152:155], v[128:143]
	ds_read_b64_tr_b16 v[70:71], v209 offset:29696
	ds_read_b64_tr_b16 v[72:73], v209 offset:30208
	v_add_f32_e32 v65, v110, v65
	v_add_f32_e32 v224, v111, v224
	v_add_f32_e32 v65, v80, v65
	v_add_f32_e32 v224, v81, v224
	v_cvt_pk_bf16_f32 v170, v108, v109
	v_cvt_pk_bf16_f32 v171, v110, v111
	s_waitcnt lgkmcnt(12)
	v_mfma_f32_32x32x16_bf16 v[112:127], v[192:195], v[152:155], v[112:127]
	ds_read_b64_tr_b16 v[66:67], v209 offset:26624
	ds_read_b64_tr_b16 v[68:69], v209 offset:27136
	v_add_f32_e32 v65, v82, v65
	v_add_f32_e32 v224, v83, v224
	v_add_f32_e32 v65, v84, v65
	v_add_f32_e32 v224, v85, v224
	v_cvt_pk_bf16_f32 v164, v80, v81
	v_cvt_pk_bf16_f32 v165, v82, v83
	s_waitcnt lgkmcnt(13)
	v_mfma_f32_32x32x16_bf16 v[128:143], v[188:191], v[148:151], v[128:143]
	ds_read_b64_tr_b16 v[100:101], v209 offset:30720
	ds_read_b64_tr_b16 v[102:103], v209 offset:31232
	v_add_f32_e32 v65, v86, v65
	v_add_f32_e32 v224, v87, v224
	v_add_f32_e32 v65, v88, v65
	v_add_f32_e32 v224, v89, v224
	v_cvt_pk_bf16_f32 v166, v84, v85
	v_cvt_pk_bf16_f32 v167, v86, v87
	s_waitcnt lgkmcnt(14)
	v_mfma_f32_32x32x16_bf16 v[112:127], v[184:187], v[148:151], v[112:127]
	ds_read_b64_tr_b16 v[96:97], v209 offset:27648
	ds_read_b64_tr_b16 v[98:99], v209 offset:28160
	v_add_f32_e32 v65, v90, v65
	v_add_f32_e32 v224, v91, v224
	v_add_f32_e32 v65, v92, v65
	v_add_f32_e32 v224, v93, v224
	v_cvt_pk_bf16_f32 v160, v88, v89
	v_cvt_pk_bf16_f32 v161, v90, v91
	s_waitcnt lgkmcnt(14)
	v_mfma_f32_32x32x16_bf16 v[128:143], v[180:183], v[144:147], v[128:143]
	ds_read_b64_tr_b16 v[86:87], v209 offset:31744
	ds_read_b64_tr_b16 v[88:89], v209 offset:32256
	v_add_f32_e32 v65, v94, v65
	v_add_f32_e32 v224, v95, v224
	v_add_f32_e32 v65, v224, v65
	v_cvt_pk_bf16_f32 v162, v92, v93
	v_cvt_pk_bf16_f32 v163, v94, v95
	v_mfma_f32_32x32x16_bf16 v[112:127], v[176:179], v[144:147], v[112:127]
	v_lshl_add_u64 v[190:191], v[212:213], 0, s[48:49]
	v_lshl_add_u64 v[78:79], v[190:191], 0, s[10:11]
	s_add_i32 s5, s42, s3
	s_mov_b32 s6, m0
	s_mov_b32 m0, s5
	s_nop 0
	global_load_lds_dwordx4 v[78:79], off
	s_mov_b32 m0, s6
	v_lshl_add_u64 v[188:189], v[210:211], 0, s[48:49]
	v_lshl_add_u64 v[78:79], v[188:189], 0, s[12:13]
	s_add_i32 s5, s36, s97
	s_mov_b32 s6, m0
	s_mov_b32 m0, s5
	s_nop 0
	global_load_lds_dwordx4 v[78:79], off
	s_mov_b32 m0, s6
	v_lshl_add_u64 v[78:79], v[188:189], 0, s[14:15]
	s_add_i32 s5, s36, s96
	s_mov_b32 s6, m0
	s_mov_b32 m0, s5
	s_nop 0
	global_load_lds_dwordx4 v[78:79], off
	s_mov_b32 m0, s6
	s_waitcnt lgkmcnt(14)
	v_mfma_f32_32x32x16_bf16 v[32:47], v[172:175], v[216:219], v[32:47]
	v_exp_f32_e32 v128, v128
	v_exp_f32_e32 v129, v129
	ds_read_b64_tr_b16 v[90:91], v209 offset:49152
	ds_read_b64_tr_b16 v[92:93], v209 offset:49664
	s_waitcnt lgkmcnt(14)
	v_mfma_f32_32x32x16_bf16 v[48:63], v[172:175], v[204:207], v[48:63]
	v_exp_f32_e32 v130, v130
	v_exp_f32_e32 v131, v131
	ds_read_b64_tr_b16 v[104:105], v209 offset:53248
	ds_read_b64_tr_b16 v[106:107], v209 offset:53760
	v_add_u32_e32 v94, s37, v250
	ds_read_b128 v[82:85], v94
	ds_read_b128 v[78:81], v94 offset:512
	s_waitcnt lgkmcnt(14)
	v_mfma_f32_32x32x16_bf16 v[32:47], v[168:171], v[74:77], v[32:47]
	v_exp_f32_e32 v132, v132
	v_exp_f32_e32 v133, v133
	ds_read_b64_tr_b16 v[108:109], v209 offset:50176
	ds_read_b64_tr_b16 v[110:111], v209 offset:50688
	ds_read_b128 v[184:187], v94 offset:2048
	ds_read_b128 v[176:179], v94 offset:2560
	v_mfma_f32_32x32x16_bf16 v[48:63], v[168:171], v[70:73], v[48:63]
	v_exp_f32_e32 v134, v134
	v_exp_f32_e32 v135, v135
	ds_read_b64_tr_b16 v[192:193], v209 offset:54272
	ds_read_b64_tr_b16 v[194:195], v209 offset:54784
	ds_read_b128 v[180:183], v94 offset:4096
	ds_read_b128 v[70:73], v94 offset:4608
	s_waitcnt lgkmcnt(14)
	v_mfma_f32_32x32x16_bf16 v[32:47], v[164:167], v[66:69], v[32:47]
	v_exp_f32_e32 v136, v136
	v_exp_f32_e32 v137, v137
	ds_read_b64_tr_b16 v[196:197], v209 offset:51200
	ds_read_b64_tr_b16 v[198:199], v209 offset:51712
	ds_read_b128 v[74:77], v94 offset:6144
	ds_read_b128 v[66:69], v94 offset:6656
	v_mfma_f32_32x32x16_bf16 v[48:63], v[164:167], v[100:103], v[48:63]
	v_exp_f32_e32 v138, v138
	v_exp_f32_e32 v139, v139
	ds_read_b64_tr_b16 v[100:101], v209 offset:55296
	ds_read_b64_tr_b16 v[102:103], v209 offset:55808
	v_mfma_f32_32x32x16_bf16 v[32:47], v[160:163], v[96:99], v[32:47]
	v_exp_f32_e32 v140, v140
	v_exp_f32_e32 v141, v141
	ds_read_b64_tr_b16 v[94:95], v209 offset:52224
	ds_read_b64_tr_b16 v[96:97], v209 offset:52736
	v_mfma_f32_32x32x16_bf16 v[48:63], v[160:163], v[86:89], v[48:63]
	v_exp_f32_e32 v142, v142
	v_exp_f32_e32 v143, v143
	ds_read_b64_tr_b16 v[86:87], v209 offset:56320
	ds_read_b64_tr_b16 v[88:89], v209 offset:56832
	s_waitcnt lgkmcnt(14)
	v_mfma_f32_32x32x16_bf16 v[0:15], v[172:175], v[90:93], v[0:15]
	v_exp_f32_e32 v112, v112
	v_exp_f32_e32 v113, v113
	v_mfma_f32_32x32x16_bf16 v[16:31], v[172:175], v[104:107], v[16:31]
	v_exp_f32_e32 v114, v114
	v_exp_f32_e32 v115, v115
	v_mfma_f32_32x32x16_bf16 v[0:15], v[168:171], v[108:111], v[0:15]
	v_exp_f32_e32 v116, v116
	v_exp_f32_e32 v117, v117
	s_waitcnt lgkmcnt(12)
	v_mfma_f32_32x32x16_bf16 v[16:31], v[168:171], v[192:195], v[16:31]
	v_exp_f32_e32 v118, v118
	v_exp_f32_e32 v119, v119
	s_waitcnt lgkmcnt(8)
	v_mfma_f32_32x32x16_bf16 v[0:15], v[164:167], v[196:199], v[0:15]
	v_exp_f32_e32 v120, v120
	v_exp_f32_e32 v121, v121
	s_waitcnt lgkmcnt(4)
	v_mfma_f32_32x32x16_bf16 v[16:31], v[164:167], v[100:103], v[16:31]
	v_exp_f32_e32 v122, v122
	v_exp_f32_e32 v123, v123
	s_waitcnt lgkmcnt(2)
	v_mfma_f32_32x32x16_bf16 v[0:15], v[160:163], v[94:97], v[0:15]
	v_exp_f32_e32 v124, v124
	v_exp_f32_e32 v125, v125
	s_waitcnt lgkmcnt(0)
	v_mfma_f32_32x32x16_bf16 v[16:31], v[160:163], v[86:89], v[16:31]
	v_exp_f32_e32 v126, v126
	v_exp_f32_e32 v127, v127
	s_waitcnt vmcnt(3) lgkmcnt(0)
	s_barrier
	s_add_i32 s5, s36, 0x2000
	s_cmpk_lg_i32 s36, 0x4000
	s_cselect_b32 s42, s5, 0
	v_add_u32_e32 v209, s1, v252
	ds_read_b64_tr_b16 v[192:193], v209 offset:24576
	ds_read_b64_tr_b16 v[194:195], v209 offset:25088
	v_mfma_f32_32x32x16_bf16 v[96:111], v[82:85], v[156:159], v[230:245]
	v_add_f32_e32 v86, v128, v129
	v_add_f32_e32 v225, v130, v131
	v_add_f32_e32 v86, v132, v86
	v_add_f32_e32 v225, v133, v225
	s_nop 0
	v_cvt_pk_bf16_f32 v172, v128, v129
	v_cvt_pk_bf16_f32 v173, v130, v131
	ds_read_b64_tr_b16 v[196:197], v209 offset:28672
	ds_read_b64_tr_b16 v[198:199], v209 offset:29184
	v_add_f32_e32 v82, v134, v86
	v_add_f32_e32 v225, v135, v225
	v_add_f32_e32 v128, v136, v82
	v_add_f32_e32 v225, v137, v225
	v_mfma_f32_32x32x16_bf16 v[80:95], v[78:81], v[156:159], v[230:245]
	v_cvt_pk_bf16_f32 v174, v132, v133
	v_cvt_pk_bf16_f32 v175, v134, v135
	ds_read_b64_tr_b16 v[216:217], v209 offset:25600
	ds_read_b64_tr_b16 v[218:219], v209 offset:26112
	v_mfma_f32_32x32x16_bf16 v[96:111], v[184:187], v[152:155], v[96:111]
	v_add_f32_e32 v78, v138, v128
	v_add_f32_e32 v225, v139, v225
	v_add_f32_e32 v78, v140, v78
	v_add_f32_e32 v225, v141, v225
	v_cvt_pk_bf16_f32 v168, v136, v137
	v_cvt_pk_bf16_f32 v169, v138, v139
	ds_read_b64_tr_b16 v[136:137], v209 offset:29696
	ds_read_b64_tr_b16 v[138:139], v209 offset:30208
	v_mfma_f32_32x32x16_bf16 v[80:95], v[176:179], v[152:155], v[80:95]
	v_add_f32_e32 v78, v142, v78
	v_add_f32_e32 v225, v143, v225
	v_add_f32_e32 v78, v112, v78
	v_add_f32_e32 v225, v113, v225
	v_cvt_pk_bf16_f32 v170, v140, v141
	v_cvt_pk_bf16_f32 v171, v142, v143
	ds_read_b64_tr_b16 v[132:133], v209 offset:26624
	ds_read_b64_tr_b16 v[134:135], v209 offset:27136
	v_mfma_f32_32x32x16_bf16 v[96:111], v[180:183], v[148:151], v[96:111]
	v_add_f32_e32 v78, v114, v78
	v_add_f32_e32 v225, v115, v225
	v_add_f32_e32 v78, v116, v78
	v_add_f32_e32 v225, v117, v225
	v_cvt_pk_bf16_f32 v164, v112, v113
	v_cvt_pk_bf16_f32 v165, v114, v115
	ds_read_b64_tr_b16 v[128:129], v209 offset:30720
	ds_read_b64_tr_b16 v[130:131], v209 offset:31232
	v_mfma_f32_32x32x16_bf16 v[80:95], v[70:73], v[148:151], v[80:95]
	v_add_f32_e32 v78, v118, v78
	v_add_f32_e32 v225, v119, v225
	v_add_f32_e32 v78, v120, v78
	v_add_f32_e32 v225, v121, v225
	v_cvt_pk_bf16_f32 v166, v116, v117
	v_cvt_pk_bf16_f32 v167, v118, v119
	ds_read_b64_tr_b16 v[112:113], v209 offset:27648
	ds_read_b64_tr_b16 v[114:115], v209 offset:28160
	v_mfma_f32_32x32x16_bf16 v[96:111], v[74:77], v[144:147], v[96:111]
	v_add_f32_e32 v70, v122, v78
	v_add_f32_e32 v225, v123, v225
	v_add_f32_e32 v78, v124, v70
	v_add_f32_e32 v225, v125, v225
	v_cvt_pk_bf16_f32 v160, v120, v121
	v_cvt_pk_bf16_f32 v161, v122, v123
	ds_read_b64_tr_b16 v[70:71], v209 offset:31744
	ds_read_b64_tr_b16 v[72:73], v209 offset:32256
	v_mfma_f32_32x32x16_bf16 v[80:95], v[66:69], v[144:147], v[80:95]
	v_add_f32_e32 v74, v126, v78
	v_add_f32_e32 v225, v127, v225
	v_add_f32_e32 v74, v225, v74
	v_cvt_pk_bf16_f32 v162, v124, v125
	v_cvt_pk_bf16_f32 v163, v126, v127
	v_lshl_add_u64 v[66:67], v[190:191], 0, s[16:17]
	s_add_i32 s1, s36, s3
	s_mov_b32 s5, m0
	s_mov_b32 m0, s1
	s_nop 0
	global_load_lds_dwordx4 v[66:67], off
	s_mov_b32 m0, s5
	v_lshl_add_u64 v[66:67], v[188:189], 0, s[18:19]
	s_add_i32 s1, s42, s97
	s_mov_b32 s5, m0
	s_mov_b32 m0, s1
	s_nop 0
	global_load_lds_dwordx4 v[66:67], off
	s_mov_b32 m0, s5
	v_lshl_add_u64 v[66:67], v[188:189], 0, s[20:21]
	s_add_i32 s1, s42, s96
	s_mov_b32 s5, m0
	s_mov_b32 m0, s1
	s_nop 0
	global_load_lds_dwordx4 v[66:67], off
	s_mov_b32 m0, s5
	s_waitcnt lgkmcnt(14)
; #define WAIT_BAR(N) asm volatile("s_waitcnt vmcnt(" #N ") lgkmcnt(0)\n\ts_barrier":::"memory")
;   #define RESC() do{ if(resc){ asm volatile("s_waitcnt lgkmcnt(0)":::"memory"); \
;       _Pragma("unroll") for(int d_=0;d_<2;++d_) _Pragma("unroll") for(int r=0;r<16;++r){const float f_=wsf[crow(r,hi)];o[d_][r]*=f_;o2[d_][r]*=f_;} } }while(0)
;   #define ROT() do{sl_prev=sl_cur;sl_cur=sl_next;sl_next=(sl_next==(NSLOT-1)*SLOTB)?0:sl_next+SLOTB;}while(0)
; template<int THRL> __device__ __forceinline__ void attn_unit(int b,int h,int qb,unsigned char*wsb,char*shm,float kmax,const int CMB,float lam){
;     ...
;   int t=1;
;     ...
;   for(;t+5<NT;t+=2){
;     STEP(pB0,pB1,pA0,pA1,t,true,true,true);     WAIT_BAR(3); RESC(); ROT();
;     STEP(pA0,pA1,pB0,pB1,t+1,true,true,true);   WAIT_BAR(3); RESC(); ROT();
;   }
	v_mfma_f32_32x32x16_bf16 v[32:47], v[172:175], v[192:195], v[32:47]
	v_exp_f32_e32 v96, v96
	v_exp_f32_e32 v97, v97
	ds_read_b64_tr_b16 v[66:67], v209 offset:49152
	ds_read_b64_tr_b16 v[68:69], v209 offset:49664
	s_waitcnt lgkmcnt(14)
	v_mfma_f32_32x32x16_bf16 v[48:63], v[172:175], v[196:199], v[48:63]
	v_exp_f32_e32 v98, v98
	v_exp_f32_e32 v99, v99
	ds_read_b64_tr_b16 v[76:77], v209 offset:53248
	ds_read_b64_tr_b16 v[78:79], v209 offset:53760
	v_add_u32_e32 v75, s42, v250
	ds_read_b128 v[204:207], v75
	ds_read_b128 v[200:203], v75 offset:512
	s_waitcnt lgkmcnt(14)
	v_mfma_f32_32x32x16_bf16 v[32:47], v[168:171], v[216:219], v[32:47]
	v_exp_f32_e32 v100, v100
	v_exp_f32_e32 v101, v101
	ds_read_b64_tr_b16 v[116:117], v209 offset:50176
	ds_read_b64_tr_b16 v[118:119], v209 offset:50688
	ds_read_b128 v[196:199], v75 offset:2048
	ds_read_b128 v[192:195], v75 offset:2560
	v_mfma_f32_32x32x16_bf16 v[48:63], v[168:171], v[136:139], v[48:63]
	v_exp_f32_e32 v102, v102
	v_exp_f32_e32 v103, v103
	ds_read_b64_tr_b16 v[120:121], v209 offset:54272
	ds_read_b64_tr_b16 v[122:123], v209 offset:54784
	ds_read_b128 v[188:191], v75 offset:4096
	ds_read_b128 v[184:187], v75 offset:4608
	s_waitcnt lgkmcnt(14)
	v_mfma_f32_32x32x16_bf16 v[32:47], v[164:167], v[132:135], v[32:47]
	v_exp_f32_e32 v104, v104
	v_exp_f32_e32 v105, v105
	ds_read_b64_tr_b16 v[124:125], v209 offset:51200
	ds_read_b64_tr_b16 v[126:127], v209 offset:51712
	ds_read_b128 v[180:183], v75 offset:6144
	ds_read_b128 v[176:179], v75 offset:6656
	v_mfma_f32_32x32x16_bf16 v[48:63], v[164:167], v[128:131], v[48:63]
	v_exp_f32_e32 v106, v106
	v_exp_f32_e32 v107, v107
	ds_read_b64_tr_b16 v[128:129], v209 offset:55296
	ds_read_b64_tr_b16 v[130:131], v209 offset:55808
	v_mfma_f32_32x32x16_bf16 v[32:47], v[160:163], v[112:115], v[32:47]
	v_exp_f32_e32 v108, v108
	v_exp_f32_e32 v109, v109
	ds_read_b64_tr_b16 v[112:113], v209 offset:52224
	ds_read_b64_tr_b16 v[114:115], v209 offset:52736
	v_mfma_f32_32x32x16_bf16 v[48:63], v[160:163], v[70:73], v[48:63]
	v_exp_f32_e32 v110, v110
	v_exp_f32_e32 v111, v111
	ds_read_b64_tr_b16 v[70:71], v209 offset:56320
	ds_read_b64_tr_b16 v[72:73], v209 offset:56832
	s_waitcnt lgkmcnt(14)
	v_mfma_f32_32x32x16_bf16 v[0:15], v[172:175], v[66:69], v[0:15]
	v_exp_f32_e32 v80, v80
	v_exp_f32_e32 v81, v81
	v_mfma_f32_32x32x16_bf16 v[16:31], v[172:175], v[76:79], v[16:31]
	v_exp_f32_e32 v82, v82
	v_exp_f32_e32 v83, v83
	v_mfma_f32_32x32x16_bf16 v[0:15], v[168:171], v[116:119], v[0:15]
	v_exp_f32_e32 v84, v84
	v_exp_f32_e32 v85, v85
	s_waitcnt lgkmcnt(12)
	v_mfma_f32_32x32x16_bf16 v[16:31], v[168:171], v[120:123], v[16:31]
	v_exp_f32_e32 v86, v86
	v_exp_f32_e32 v87, v87
	s_waitcnt lgkmcnt(8)
	v_mfma_f32_32x32x16_bf16 v[0:15], v[164:167], v[124:127], v[0:15]
	v_exp_f32_e32 v88, v88
	v_exp_f32_e32 v89, v89
	s_waitcnt lgkmcnt(4)
	v_mfma_f32_32x32x16_bf16 v[16:31], v[164:167], v[128:131], v[16:31]
	v_exp_f32_e32 v90, v90
	v_exp_f32_e32 v91, v91
	s_waitcnt lgkmcnt(2)
	v_mfma_f32_32x32x16_bf16 v[0:15], v[160:163], v[112:115], v[0:15]
	v_exp_f32_e32 v92, v92
	v_exp_f32_e32 v93, v93
	s_waitcnt lgkmcnt(0)
	v_mfma_f32_32x32x16_bf16 v[16:31], v[160:163], v[70:73], v[16:31]
	v_exp_f32_e32 v94, v94
	v_exp_f32_e32 v95, v95
	s_add_i32 s1, s42, 0x2000
	s_waitcnt vmcnt(3) lgkmcnt(0)
	s_barrier
	s_cmpk_lg_i32 s42, 0x4000
	v_add_f32_e32 v64, v64, v65
	s_mov_b32 s5, s36
	s_cselect_b32 s36, s1, 0
	s_add_i32 s33, s33, 2
	v_lshl_add_u64 v[210:211], v[210:211], 0, s[22:23]
	v_lshl_add_u64 v[212:213], v[212:213], 0, s[22:23]
	s_cmp_ge_u32 s33, s89
	v_add_f32_e32 v64, v64, v74
	s_cbranch_scc0 .LBB0_311
	ds_read_b32 v230, v246
	ds_read_b32 v231, v246 offset:2048
	ds_read_b32 v232, v246 offset:4096
	ds_read_b32 v233, v246 offset:6144
	ds_read_b32 v234, v246 offset:8192
	ds_read_b32 v235, v246 offset:10240
	ds_read_b32 v236, v246 offset:12288
	ds_read_b32 v237, v246 offset:14336
	ds_read_b32 v238, v246 offset:16384
	ds_read_b32 v239, v246 offset:18432
	ds_read_b32 v240, v246 offset:20480
	ds_read_b32 v241, v246 offset:22528
	ds_read_b32 v242, v246 offset:24576
	ds_read_b32 v243, v246 offset:26624
	ds_read_b32 v244, v246 offset:28672
	ds_read_b32 v245, v246 offset:30720
	ds_read_b32 v246, v246 offset:32768
	s_waitcnt lgkmcnt(0)
	s_add_i32 s6, s4, -3
	s_branch .LBB0_314
